# stagger45 without the store drain before the tail-first workgroups re-enter the main tile
# speedup vs baseline: 1.0034x; 1.0034x over previous
.LBB0_1027:
	s_ashr_i32 s9, s16, 5
	s_lshl_b32 s17, s9, 6
	s_and_b32 s8, s3, 0xc0
	s_and_b32 s17, s17, 0xffffff00
	s_or_b32 s8, s8, s17
	s_lshl_b32 s9, s9, 8
	v_add_u32_e32 v0, s8, v14
	s_and_b32 s18, s9, 0x300
	v_mad_i64_i32 v[10:11], s[8:9], v0, s15, v[6:7]
	s_lshl_b32 s8, s13, 11
	v_or_b32_e32 v0, s18, v16
	s_and_b32 s8, s8, 0x70000
	v_lshl_or_b32 v4, v0, 11, s8
	v_lshl_add_u64 v[12:13], v[8:9], 0, v[4:5]
	v_mov_b32_e32 v176, v12
	v_mov_b32_e32 v177, v13
	v_mov_b32_e32 v178, v10
	v_mov_b32_e32 v179, v11
	s_lshl_b32 s8, s16, 3
	s_and_b32 s8, s8, 0xc0
	s_lshl_b32 s9, s16, 5
	s_add_i32 s17, s17, s8
	s_and_b32 s9, s9, 0xe0
	v_add_u32_e32 v10, s17, v14
	s_or_b32 s9, s18, s9
	v_ashrrev_i32_e32 v11, 31, v10
	v_or_b32_e32 v4, s9, v15
	v_lshlrev_b64 v[10:11], 11, v[10:11]
	v_lshl_or_b32 v10, v4, 1, v10
	v_lshl_add_u64 v[12:13], s[4:5], 0, v[10:11]
	v_lshl_add_u64 v[18:19], s[6:7], 0, v[10:11]
	global_load_dwordx2 v[12:13], v[12:13], off
	global_load_dwordx2 v[18:19], v[18:19], off
	v_lshl_add_u64 v[10:11], s[10:11], 0, v[10:11]
	v_readfirstlane_b32 s20, v170
	s_nop 3
	s_lshr_b32 s20, s20, 6
	s_and_b32 s21, s20, 1
	s_lshr_b32 s22, s20, 1
	s_lshl_b32 s23, s20, 8
	s_lshl_b32 s28, s21, 15
	s_sub_u32 s24, s23, s28
	s_subb_u32 s25, 0, 0
	s_mul_i32 s28, s22, 98304
	s_add_u32 s29, s23, 4096
	s_sub_u32 s26, s29, s28
	s_subb_u32 s27, 0, 0
	v_lshl_add_u64 v[172:173], v[176:177], 0, s[24:25]
	v_lshl_add_u64 v[84:85], v[178:179], 0, s[26:27]
	s_mov_b64 s[28:29], 0x8000
	v_lshl_add_u64 v[174:175], v[172:173], 0, s[28:29]
	s_mov_b64 s[28:29], 98304
	v_lshl_add_u64 v[86:87], v[84:85], 0, s[28:29]
	v_lshl_add_u64 v[88:89], v[86:87], 0, s[28:29]
	v_lshl_add_u64 v[90:91], v[88:89], 0, s[28:29]
	global_load_dwordx4 v[20:23], v[84:85], off offset:0
	global_load_dwordx4 v[24:27], v[86:87], off offset:0
	global_load_dwordx4 v[28:31], v[88:89], off offset:0
	global_load_dwordx4 v[32:35], v[90:91], off offset:0
	global_load_dwordx4 v[36:39], v[172:173], off offset:0
	global_load_dwordx4 v[40:43], v[174:175], off offset:0
	global_load_dwordx4 v[44:47], v[84:85], off offset:64
	global_load_dwordx4 v[48:51], v[86:87], off offset:64
	global_load_dwordx4 v[52:55], v[88:89], off offset:64
	global_load_dwordx4 v[56:59], v[90:91], off offset:64
	global_load_dwordx4 v[60:63], v[172:173], off offset:64
	global_load_dwordx4 v[64:67], v[174:175], off offset:64
	global_load_dwordx4 v[68:71], v[84:85], off offset:128
	global_load_dwordx4 v[72:75], v[86:87], off offset:128
	global_load_dwordx4 v[76:79], v[88:89], off offset:128
	global_load_dwordx4 v[80:83], v[90:91], off offset:128
	global_load_dwordx4 v[92:95], v[172:173], off offset:128
	global_load_dwordx4 v[96:99], v[174:175], off offset:128
	global_load_dwordx4 v[100:103], v[84:85], off offset:192
	global_load_dwordx4 v[104:107], v[86:87], off offset:192
	global_load_dwordx4 v[108:111], v[88:89], off offset:192
	global_load_dwordx4 v[112:115], v[90:91], off offset:192
	global_load_dwordx4 v[116:119], v[172:173], off offset:192
	global_load_dwordx4 v[120:123], v[174:175], off offset:192
	v_mov_b32_e32 v124, 0
	v_mov_b32_e32 v125, 0
	v_mov_b32_e32 v126, 0
	v_mov_b32_e32 v127, 0
	v_mov_b32_e32 v128, 0
	v_mov_b32_e32 v129, 0
	v_mov_b32_e32 v130, 0
	v_mov_b32_e32 v131, 0
	v_mov_b32_e32 v132, 0
	v_mov_b32_e32 v133, 0
	v_mov_b32_e32 v134, 0
	v_mov_b32_e32 v135, 0
	v_mov_b32_e32 v136, 0
	v_mov_b32_e32 v137, 0
	v_mov_b32_e32 v138, 0
	v_mov_b32_e32 v139, 0
	v_mov_b32_e32 v140, 0
	v_mov_b32_e32 v141, 0
	v_mov_b32_e32 v142, 0
	v_mov_b32_e32 v143, 0
	v_mov_b32_e32 v144, 0
	v_mov_b32_e32 v145, 0
	v_mov_b32_e32 v146, 0
	v_mov_b32_e32 v147, 0
	v_mov_b32_e32 v148, 0
	v_mov_b32_e32 v149, 0
	v_mov_b32_e32 v150, 0
	v_mov_b32_e32 v151, 0
	v_mov_b32_e32 v152, 0
	v_mov_b32_e32 v153, 0
	v_mov_b32_e32 v154, 0
	v_mov_b32_e32 v155, 0
	v_and_b32_e32 v156, 63, v170
	v_lshlrev_b32_e32 v156, 4, v156
	s_lshl_b32 s28, s20, 10
	v_add_u32_e32 v157, s28, v156
	s_lshl_b32 s28, s20, 13
	v_add_u32_e32 v158, s28, v156
	s_waitcnt vmcnt(18)
	v_mfma_f32_16x16x32_bf16 v[124:127], v[36:39], v[20:23], v[124:127]
	v_mfma_f32_16x16x32_bf16 v[128:131], v[40:43], v[20:23], v[128:131]
	v_mfma_f32_16x16x32_bf16 v[132:135], v[36:39], v[24:27], v[132:135]
	v_mfma_f32_16x16x32_bf16 v[136:139], v[40:43], v[24:27], v[136:139]
	v_mfma_f32_16x16x32_bf16 v[140:143], v[36:39], v[28:31], v[140:143]
	v_mfma_f32_16x16x32_bf16 v[144:147], v[40:43], v[28:31], v[144:147]
	v_mfma_f32_16x16x32_bf16 v[148:151], v[36:39], v[32:35], v[148:151]
	v_mfma_f32_16x16x32_bf16 v[152:155], v[40:43], v[32:35], v[152:155]
	s_waitcnt vmcnt(12)
	v_mfma_f32_16x16x32_bf16 v[124:127], v[60:63], v[44:47], v[124:127]
	v_mfma_f32_16x16x32_bf16 v[128:131], v[64:67], v[44:47], v[128:131]
	v_mfma_f32_16x16x32_bf16 v[132:135], v[60:63], v[48:51], v[132:135]
	v_mfma_f32_16x16x32_bf16 v[136:139], v[64:67], v[48:51], v[136:139]
	v_mfma_f32_16x16x32_bf16 v[140:143], v[60:63], v[52:55], v[140:143]
	v_mfma_f32_16x16x32_bf16 v[144:147], v[64:67], v[52:55], v[144:147]
	v_mfma_f32_16x16x32_bf16 v[148:151], v[60:63], v[56:59], v[148:151]
	v_mfma_f32_16x16x32_bf16 v[152:155], v[64:67], v[56:59], v[152:155]
	s_waitcnt vmcnt(6)
	v_mfma_f32_16x16x32_bf16 v[124:127], v[92:95], v[68:71], v[124:127]
	v_mfma_f32_16x16x32_bf16 v[128:131], v[96:99], v[68:71], v[128:131]
	v_mfma_f32_16x16x32_bf16 v[132:135], v[92:95], v[72:75], v[132:135]
	v_mfma_f32_16x16x32_bf16 v[136:139], v[96:99], v[72:75], v[136:139]
	v_mfma_f32_16x16x32_bf16 v[140:143], v[92:95], v[76:79], v[140:143]
	v_mfma_f32_16x16x32_bf16 v[144:147], v[96:99], v[76:79], v[144:147]
	v_mfma_f32_16x16x32_bf16 v[148:151], v[92:95], v[80:83], v[148:151]
	v_mfma_f32_16x16x32_bf16 v[152:155], v[96:99], v[80:83], v[152:155]
	s_waitcnt vmcnt(0)
	v_mfma_f32_16x16x32_bf16 v[124:127], v[116:119], v[100:103], v[124:127]
	v_mfma_f32_16x16x32_bf16 v[128:131], v[120:123], v[100:103], v[128:131]
	v_mfma_f32_16x16x32_bf16 v[132:135], v[116:119], v[104:107], v[132:135]
	v_mfma_f32_16x16x32_bf16 v[136:139], v[120:123], v[104:107], v[136:139]
	v_mfma_f32_16x16x32_bf16 v[140:143], v[116:119], v[108:111], v[140:143]
	v_mfma_f32_16x16x32_bf16 v[144:147], v[120:123], v[108:111], v[144:147]
	v_mfma_f32_16x16x32_bf16 v[148:151], v[116:119], v[112:115], v[148:151]
	v_mfma_f32_16x16x32_bf16 v[152:155], v[120:123], v[112:115], v[152:155]
	s_nop 8
	ds_write_b128 v157, v[124:127] offset:0
	ds_write_b128 v157, v[128:131] offset:8192
	ds_write_b128 v157, v[132:135] offset:16384
	ds_write_b128 v157, v[136:139] offset:24576
	ds_write_b128 v157, v[140:143] offset:32768
	ds_write_b128 v157, v[144:147] offset:40960
	ds_write_b128 v157, v[148:151] offset:49152
	ds_write_b128 v157, v[152:155] offset:57344
	s_waitcnt lgkmcnt(0)
	s_barrier
	ds_read_b128 v[20:23], v158 offset:0
	ds_read_b128 v[24:27], v158 offset:1024
	ds_read_b128 v[28:31], v158 offset:2048
	ds_read_b128 v[32:35], v158 offset:3072
	ds_read_b128 v[36:39], v158 offset:4096
	ds_read_b128 v[40:43], v158 offset:5120
	ds_read_b128 v[44:47], v158 offset:6144
	ds_read_b128 v[48:51], v158 offset:7168
	s_waitcnt lgkmcnt(0)
	v_pk_add_f32 v[0:1], v[20:21], v[24:25]
	v_pk_add_f32 v[2:3], v[22:23], v[26:27]
	v_pk_add_f32 v[0:1], v[0:1], v[28:29]
	v_pk_add_f32 v[2:3], v[2:3], v[30:31]
	v_pk_add_f32 v[0:1], v[0:1], v[32:33]
	v_pk_add_f32 v[2:3], v[2:3], v[34:35]
	v_pk_add_f32 v[0:1], v[0:1], v[36:37]
	v_pk_add_f32 v[2:3], v[2:3], v[38:39]
	v_pk_add_f32 v[0:1], v[0:1], v[40:41]
	v_pk_add_f32 v[2:3], v[2:3], v[42:43]
	v_pk_add_f32 v[0:1], v[0:1], v[44:45]
	v_pk_add_f32 v[2:3], v[2:3], v[46:47]
	v_pk_add_f32 v[0:1], v[0:1], v[48:49]
	v_pk_add_f32 v[2:3], v[2:3], v[50:51]
	s_add_i32 s16, s16, s30
	s_add_i32 s3, s3, s12
	s_add_i32 s13, s13, s14
	s_cmpk_gt_i32 s16, 0xff
	s_waitcnt vmcnt(0)
	v_lshlrev_b32_e32 v20, 16, v12
	v_and_b32_e32 v21, 0xffff0000, v12
	v_lshlrev_b32_e32 v22, 16, v18
	v_and_b32_e32 v23, 0xffff0000, v18
	v_lshlrev_b32_e32 v12, 16, v13
	v_and_b32_e32 v13, 0xffff0000, v13
	v_lshlrev_b32_e32 v18, 16, v19
	v_and_b32_e32 v19, 0xffff0000, v19
	v_pk_fma_f32 v[0:1], v[0:1], v[22:23], v[20:21]
	v_pk_fma_f32 v[2:3], v[2:3], v[18:19], v[12:13]
	v_cvt_pk_bf16_f32 v0, v0, v1
	v_cvt_pk_bf16_f32 v1, v2, v3
	global_store_dwordx2 v[10:11], v[0:1], off
	s_cbranch_scc0 .LBB0_1027
	s_cmp_lg_u32 s98, 1
	s_cbranch_scc1 .LBB0_1030
	s_mov_b32 s98, 2
	s_waitcnt lgkmcnt(0)
	s_barrier
	s_branch .Lmy_p4_top

.LBB0_1130:
	s_ashr_i32 s13, s18, 5
	s_lshl_b32 s19, s13, 6
	s_lshl_b32 s13, s13, 8
	s_and_b32 s12, s16, 0xc0
	s_and_b32 s20, s19, 0xffffff00
	s_and_b32 s19, s13, 0x300
	s_lshl_b32 s13, s14, 11
	v_or_b32_e32 v0, s19, v17
	s_and_b32 s13, s13, 0x70000
	s_or_b32 s12, s12, s20
	v_lshl_or_b32 v4, v0, 11, s13
	v_add_u32_e32 v0, s12, v18
	v_ashrrev_i32_e32 v1, 31, v0
	v_lshlrev_b64 v[0:1], 11, v[0:1]
	v_lshl_add_u64 v[10:11], v[6:7], 0, v[4:5]
	v_lshl_add_u64 v[12:13], v[8:9], 0, v[0:1]
	v_mov_b32_e32 v176, v10
	v_mov_b32_e32 v177, v11
	v_mov_b32_e32 v178, v12
	v_mov_b32_e32 v179, v13
	s_lshl_b32 s12, s18, 3
	s_and_b32 s12, s12, 0xc0
	s_add_i32 s20, s20, s12
	v_add_u32_e32 v4, s20, v15
	v_or_b32_e32 v10, v4, v14
	s_lshl_b32 s12, s18, 5
	v_ashrrev_i32_e32 v11, 31, v10
	s_and_b32 s12, s12, 0xe0
	v_lshlrev_b64 v[20:21], 12, v[10:11]
	s_or_b32 s12, s19, s12
	v_lshl_add_u64 v[12:13], s[6:7], 0, v[20:21]
	v_or_b32_e32 v19, s12, v16
	v_lshl_add_u64 v[10:11], s[4:5], 0, v[20:21]
	v_lshl_add_u64 v[12:13], v[12:13], 0, s[10:11]
	v_cmp_gt_u32_e32 vcc, s3, v4
	v_lshlrev_b32_e32 v4, 2, v19
	s_nop 1
	v_cndmask_b32_e32 v11, v13, v11, vcc
	v_cndmask_b32_e32 v10, v12, v10, vcc
	v_lshl_add_u64 v[10:11], v[10:11], 0, v[4:5]
	global_load_dwordx4 v[10:13], v[10:11], off
	v_lshl_add_u64 v[20:21], s[8:9], 0, v[20:21]
	v_lshl_add_u64 v[20:21], v[20:21], 0, v[4:5]
	v_readfirstlane_b32 s88, v170
	s_nop 3
	s_lshr_b32 s88, s88, 6
	s_and_b32 s89, s88, 1
	s_lshr_b32 s90, s88, 1
	s_lshl_b32 s91, s88, 8
	s_lshl_b32 s96, s89, 15
	s_sub_u32 s92, s91, s96
	s_subb_u32 s93, 0, 0
	s_mul_i32 s96, s90, 32768
	s_add_u32 s97, s91, 0
	s_sub_u32 s94, s97, s96
	s_subb_u32 s95, 0, 0
	v_lshl_add_u64 v[172:173], v[176:177], 0, s[92:93]
	v_lshl_add_u64 v[84:85], v[178:179], 0, s[94:95]
	s_mov_b64 s[96:97], 0x8000
	v_lshl_add_u64 v[174:175], v[172:173], 0, s[96:97]
	s_mov_b64 s[96:97], 32768
	v_lshl_add_u64 v[86:87], v[84:85], 0, s[96:97]
	v_lshl_add_u64 v[88:89], v[86:87], 0, s[96:97]
	v_lshl_add_u64 v[90:91], v[88:89], 0, s[96:97]
	global_load_dwordx4 v[24:27], v[84:85], off offset:0
	global_load_dwordx4 v[28:31], v[86:87], off offset:0
	global_load_dwordx4 v[32:35], v[88:89], off offset:0
	global_load_dwordx4 v[36:39], v[90:91], off offset:0
	global_load_dwordx4 v[40:43], v[172:173], off offset:0
	global_load_dwordx4 v[44:47], v[174:175], off offset:0
	global_load_dwordx4 v[48:51], v[84:85], off offset:64
	global_load_dwordx4 v[52:55], v[86:87], off offset:64
	global_load_dwordx4 v[56:59], v[88:89], off offset:64
	global_load_dwordx4 v[60:63], v[90:91], off offset:64
	global_load_dwordx4 v[64:67], v[172:173], off offset:64
	global_load_dwordx4 v[68:71], v[174:175], off offset:64
	global_load_dwordx4 v[72:75], v[84:85], off offset:128
	global_load_dwordx4 v[76:79], v[86:87], off offset:128
	global_load_dwordx4 v[80:83], v[88:89], off offset:128
	global_load_dwordx4 v[92:95], v[90:91], off offset:128
	global_load_dwordx4 v[96:99], v[172:173], off offset:128
	global_load_dwordx4 v[100:103], v[174:175], off offset:128
	global_load_dwordx4 v[104:107], v[84:85], off offset:192
	global_load_dwordx4 v[108:111], v[86:87], off offset:192
	global_load_dwordx4 v[112:115], v[88:89], off offset:192
	global_load_dwordx4 v[116:119], v[90:91], off offset:192
	global_load_dwordx4 v[120:123], v[172:173], off offset:192
	global_load_dwordx4 v[124:127], v[174:175], off offset:192
	v_mov_b32_e32 v128, 0
	v_mov_b32_e32 v129, 0
	v_mov_b32_e32 v130, 0
	v_mov_b32_e32 v131, 0
	v_mov_b32_e32 v132, 0
	v_mov_b32_e32 v133, 0
	v_mov_b32_e32 v134, 0
	v_mov_b32_e32 v135, 0
	v_mov_b32_e32 v136, 0
	v_mov_b32_e32 v137, 0
	v_mov_b32_e32 v138, 0
	v_mov_b32_e32 v139, 0
	v_mov_b32_e32 v140, 0
	v_mov_b32_e32 v141, 0
	v_mov_b32_e32 v142, 0
	v_mov_b32_e32 v143, 0
	v_mov_b32_e32 v144, 0
	v_mov_b32_e32 v145, 0
	v_mov_b32_e32 v146, 0
	v_mov_b32_e32 v147, 0
	v_mov_b32_e32 v148, 0
	v_mov_b32_e32 v149, 0
	v_mov_b32_e32 v150, 0
	v_mov_b32_e32 v151, 0
	v_mov_b32_e32 v152, 0
	v_mov_b32_e32 v153, 0
	v_mov_b32_e32 v154, 0
	v_mov_b32_e32 v155, 0
	v_mov_b32_e32 v156, 0
	v_mov_b32_e32 v157, 0
	v_mov_b32_e32 v158, 0
	v_mov_b32_e32 v159, 0
	v_and_b32_e32 v160, 63, v170
	v_lshlrev_b32_e32 v160, 4, v160
	s_lshl_b32 s96, s88, 10
	v_add_u32_e32 v161, s96, v160
	s_lshl_b32 s96, s88, 13
	v_add_u32_e32 v162, s96, v160
	s_waitcnt vmcnt(18)
	v_mfma_f32_16x16x32_bf16 v[128:131], v[40:43], v[24:27], v[128:131]
	v_mfma_f32_16x16x32_bf16 v[132:135], v[44:47], v[24:27], v[132:135]
	v_mfma_f32_16x16x32_bf16 v[136:139], v[40:43], v[28:31], v[136:139]
	v_mfma_f32_16x16x32_bf16 v[140:143], v[44:47], v[28:31], v[140:143]
	v_mfma_f32_16x16x32_bf16 v[144:147], v[40:43], v[32:35], v[144:147]
	v_mfma_f32_16x16x32_bf16 v[148:151], v[44:47], v[32:35], v[148:151]
	v_mfma_f32_16x16x32_bf16 v[152:155], v[40:43], v[36:39], v[152:155]
	v_mfma_f32_16x16x32_bf16 v[156:159], v[44:47], v[36:39], v[156:159]
	s_waitcnt vmcnt(12)
	v_mfma_f32_16x16x32_bf16 v[128:131], v[64:67], v[48:51], v[128:131]
	v_mfma_f32_16x16x32_bf16 v[132:135], v[68:71], v[48:51], v[132:135]
	v_mfma_f32_16x16x32_bf16 v[136:139], v[64:67], v[52:55], v[136:139]
	v_mfma_f32_16x16x32_bf16 v[140:143], v[68:71], v[52:55], v[140:143]
	v_mfma_f32_16x16x32_bf16 v[144:147], v[64:67], v[56:59], v[144:147]
	v_mfma_f32_16x16x32_bf16 v[148:151], v[68:71], v[56:59], v[148:151]
	v_mfma_f32_16x16x32_bf16 v[152:155], v[64:67], v[60:63], v[152:155]
	v_mfma_f32_16x16x32_bf16 v[156:159], v[68:71], v[60:63], v[156:159]
	s_waitcnt vmcnt(6)
	v_mfma_f32_16x16x32_bf16 v[128:131], v[96:99], v[72:75], v[128:131]
	v_mfma_f32_16x16x32_bf16 v[132:135], v[100:103], v[72:75], v[132:135]
	v_mfma_f32_16x16x32_bf16 v[136:139], v[96:99], v[76:79], v[136:139]
	v_mfma_f32_16x16x32_bf16 v[140:143], v[100:103], v[76:79], v[140:143]
	v_mfma_f32_16x16x32_bf16 v[144:147], v[96:99], v[80:83], v[144:147]
	v_mfma_f32_16x16x32_bf16 v[148:151], v[100:103], v[80:83], v[148:151]
	v_mfma_f32_16x16x32_bf16 v[152:155], v[96:99], v[92:95], v[152:155]
	v_mfma_f32_16x16x32_bf16 v[156:159], v[100:103], v[92:95], v[156:159]
	s_waitcnt vmcnt(0)
	v_mfma_f32_16x16x32_bf16 v[128:131], v[120:123], v[104:107], v[128:131]
	v_mfma_f32_16x16x32_bf16 v[132:135], v[124:127], v[104:107], v[132:135]
	v_mfma_f32_16x16x32_bf16 v[136:139], v[120:123], v[108:111], v[136:139]
	v_mfma_f32_16x16x32_bf16 v[140:143], v[124:127], v[108:111], v[140:143]
	v_mfma_f32_16x16x32_bf16 v[144:147], v[120:123], v[112:115], v[144:147]
	v_mfma_f32_16x16x32_bf16 v[148:151], v[124:127], v[112:115], v[148:151]
	v_mfma_f32_16x16x32_bf16 v[152:155], v[120:123], v[116:119], v[152:155]
	v_mfma_f32_16x16x32_bf16 v[156:159], v[124:127], v[116:119], v[156:159]
	s_nop 8
	ds_write_b128 v161, v[128:131] offset:0
	ds_write_b128 v161, v[132:135] offset:8192
	ds_write_b128 v161, v[136:139] offset:16384
	ds_write_b128 v161, v[140:143] offset:24576
	ds_write_b128 v161, v[144:147] offset:32768
	ds_write_b128 v161, v[148:151] offset:40960
	ds_write_b128 v161, v[152:155] offset:49152
	ds_write_b128 v161, v[156:159] offset:57344
	s_waitcnt lgkmcnt(0)
	s_barrier
	ds_read_b128 v[24:27], v162 offset:0
	ds_read_b128 v[28:31], v162 offset:1024
	ds_read_b128 v[32:35], v162 offset:2048
	ds_read_b128 v[36:39], v162 offset:3072
	ds_read_b128 v[40:43], v162 offset:4096
	ds_read_b128 v[44:47], v162 offset:5120
	ds_read_b128 v[48:51], v162 offset:6144
	ds_read_b128 v[52:55], v162 offset:7168
	s_waitcnt lgkmcnt(0)
	v_pk_add_f32 v[0:1], v[24:25], v[28:29]
	v_pk_add_f32 v[2:3], v[26:27], v[30:31]
	v_pk_add_f32 v[0:1], v[0:1], v[32:33]
	v_pk_add_f32 v[2:3], v[2:3], v[34:35]
	v_pk_add_f32 v[0:1], v[0:1], v[36:37]
	v_pk_add_f32 v[2:3], v[2:3], v[38:39]
	v_pk_add_f32 v[0:1], v[0:1], v[40:41]
	v_pk_add_f32 v[2:3], v[2:3], v[42:43]
	v_pk_add_f32 v[0:1], v[0:1], v[44:45]
	v_pk_add_f32 v[2:3], v[2:3], v[46:47]
	v_pk_add_f32 v[0:1], v[0:1], v[48:49]
	v_pk_add_f32 v[2:3], v[2:3], v[50:51]
	v_pk_add_f32 v[0:1], v[0:1], v[52:53]
	v_pk_add_f32 v[2:3], v[2:3], v[54:55]
	s_add_i32 s18, s18, s30
	s_add_i32 s14, s14, s15
	s_add_i32 s16, s16, s17
	s_cmpk_gt_i32 s18, 0xff
	s_waitcnt vmcnt(0)
	v_pk_add_f32 v[2:3], v[2:3], v[12:13]
	v_pk_add_f32 v[0:1], v[0:1], v[10:11]
	global_store_dwordx4 v[20:21], v[0:3], off
	s_cbranch_scc0 .LBB0_1130
	s_cmp_lg_u32 s98, 1
	s_cbranch_scc1 .LBB0_1133
	s_mov_b32 s98, 2
	s_waitcnt lgkmcnt(0)
	s_barrier
	s_branch .Lmy_p5_top
